# speedup vs baseline: 1.0177x; 1.0008x over previous
; #define SCHED __builtin_amdgcn_sched_barrier(0)
; template <int EPI, bool HS = false>
; __device__ __forceinline__ void gemm_phase(const Params& p, const GemmCfg& g, char* shm, const int wave_s) {
;     ...
;       } else {
;         u16* ot = GOb + (size_t)orow0 * 2048 + (pn - 16) * 256;
;         const unsigned tb = (unsigned)((wr * 64 + fq * 4) * 2048 + wc * 32 + fr);
; #pragma unroll
;         for (int ai = 0; ai < 2; ++ai)
; #pragma unroll
;           for (int m = 0; m < 4; ++m) {
;             const f32x4 r4 = *(const f32x4*)(rsw + ai * 128 + m * 16);
; #pragma unroll
;             for (int j = 0; j < 4; ++j)
; #pragma unroll
;               for (int bj = 0; bj < 2; ++bj)
; #pragma unroll
;                 for (int n = 0; n < 2; ++n)
;                   ot[tb + (ai * 128 + m * 16 + j) * 2048 + bj * 128 + n * 16] = f2bf(r4[j] * acc[ai][bj][m][n][j] + swv[bj][n]);
;             SCHED;
;           }
.LBB0_589:
	s_mov_b32 s3, s82
	s_mov_b32 s8, -1
	s_ashr_i32 s10, s5, 3
	v_mbcnt_lo_u32_b32 v0, s8, 0
	v_mbcnt_hi_u32_b32 v0, s8, v0
	v_lshl_add_u32 v146, s3, 6, v0
	s_and_b32 s3, s1, 7
	v_ashrrev_i32_e32 v0, 2, v146
	v_lshrrev_b32_e32 v130, 2, v146
	v_and_b32_e32 v139, 0xffffffc0, v0
	v_and_b32_e32 v141, 12, v130
	v_ashrrev_i32_e32 v147, 6, v146
	v_lshlrev_b32_e32 v0, 2, v139
	v_lshlrev_b32_e32 v130, 2, v141
	v_and_b32_e32 v137, 3, v147
	v_and_b32_e32 v135, 15, v146
	v_add3_u32 v154, s12, v0, v130
	s_mov_b64 s[8:9], -1
	s_and_b64 vcc, exec, s[6:7]
	s_cbranch_vccz .LBB0_595
	s_and_b32 s1, s2, 0xffff
	s_cmp_gt_u32 s1, 15
	s_mov_b64 s[6:7], -1
	s_cbranch_scc0 .LBB0_592
	s_ashr_i32 s1, s0, 31
	v_readlane_b32 s12, v254, 47
	s_lshl_b64 s[6:7], s[0:1], 12
	v_readlane_b32 s14, v254, 49
	v_readlane_b32 s15, v254, 50
	s_add_u32 s1, s14, s6
	s_addc_u32 s6, s15, s7
	s_ashr_i32 s5, s4, 31
	s_lshl_b64 s[4:5], s[4:5], 1
	s_add_u32 s1, s1, s4
	s_addc_u32 s5, s6, s5
	s_add_u32 s4, s1, 0x13ffe000
	s_addc_u32 s5, s5, 0
	v_readlane_b32 s13, v254, 48
	v_or_b32_e32 v0, v139, v141
	v_lshlrev_b32_e32 v0, 12, v0
	v_lshl_add_u32 v0, v137, 7, v0
	v_lshl_add_u32 v0, v135, 3, v0
	v_add_u32_e32 v158, 0x1000, v0
	v_add_u32_e32 v159, 0x2000, v0
	v_add_u32_e32 v160, 0x3000, v0
	ds_read_b128 v[130:133], v154
	s_waitcnt lgkmcnt(0)
	v_fma_f32 v122, v122, v130, v138
	v_fma_f32 v126, v126, v130, v140
	v_fma_f32 v114, v114, v130, v134
	v_fma_f32 v118, v118, v130, v136
	v_cvt_pk_bf16_f32 v162, v122, v126
	v_cvt_pk_bf16_f32 v163, v114, v118
	global_store_dwordx2 v0, v[162:163], s[4:5]
	v_fma_f32 v123, v123, v131, v138
	v_fma_f32 v127, v127, v131, v140
	v_fma_f32 v115, v115, v131, v134
	v_fma_f32 v119, v119, v131, v136
	v_cvt_pk_bf16_f32 v164, v123, v127
	v_cvt_pk_bf16_f32 v165, v115, v119
	global_store_dwordx2 v158, v[164:165], s[4:5]
	v_fma_f32 v124, v124, v132, v138
	v_fma_f32 v128, v128, v132, v140
	v_fma_f32 v116, v116, v132, v134
	v_fma_f32 v120, v120, v132, v136
	v_cvt_pk_bf16_f32 v166, v124, v128
	v_cvt_pk_bf16_f32 v167, v116, v120
	global_store_dwordx2 v159, v[166:167], s[4:5]
	v_fma_f32 v125, v125, v133, v138
	v_fma_f32 v129, v129, v133, v140
	v_fma_f32 v117, v117, v133, v134
	v_fma_f32 v121, v121, v133, v136
	v_cvt_pk_bf16_f32 v168, v125, v129
	v_cvt_pk_bf16_f32 v169, v117, v121
	global_store_dwordx2 v160, v[168:169], s[4:5]
	s_add_u32 s4, s4, 0x10000
	s_addc_u32 s5, s5, 0
	ds_read_b128 v[130:133], v154 offset:64
	s_waitcnt lgkmcnt(0)
	v_fma_f32 v106, v106, v130, v138
	v_fma_f32 v110, v110, v130, v140
	v_fma_f32 v98, v98, v130, v134
	v_fma_f32 v102, v102, v130, v136
	v_cvt_pk_bf16_f32 v162, v106, v110
	v_cvt_pk_bf16_f32 v163, v98, v102
	global_store_dwordx2 v0, v[162:163], s[4:5]
	v_fma_f32 v107, v107, v131, v138
	v_fma_f32 v111, v111, v131, v140
	v_fma_f32 v99, v99, v131, v134
	v_fma_f32 v103, v103, v131, v136
	v_cvt_pk_bf16_f32 v164, v107, v111
	v_cvt_pk_bf16_f32 v165, v99, v103
	global_store_dwordx2 v158, v[164:165], s[4:5]
	v_fma_f32 v108, v108, v132, v138
	v_fma_f32 v112, v112, v132, v140
	v_fma_f32 v100, v100, v132, v134
	v_fma_f32 v104, v104, v132, v136
	v_cvt_pk_bf16_f32 v166, v108, v112
	v_cvt_pk_bf16_f32 v167, v100, v104
	global_store_dwordx2 v159, v[166:167], s[4:5]
	v_fma_f32 v109, v109, v133, v138
	v_fma_f32 v113, v113, v133, v140
	v_fma_f32 v101, v101, v133, v134
	v_fma_f32 v105, v105, v133, v136
	v_cvt_pk_bf16_f32 v168, v109, v113
	v_cvt_pk_bf16_f32 v169, v101, v105
	global_store_dwordx2 v160, v[168:169], s[4:5]
	s_add_u32 s4, s4, 0x10000
	s_addc_u32 s5, s5, 0
	ds_read_b128 v[130:133], v154 offset:128
	s_waitcnt lgkmcnt(0)
	v_fma_f32 v90, v90, v130, v138
	v_fma_f32 v94, v94, v130, v140
	v_fma_f32 v82, v82, v130, v134
	v_fma_f32 v86, v86, v130, v136
	v_cvt_pk_bf16_f32 v162, v90, v94
	v_cvt_pk_bf16_f32 v163, v82, v86
	global_store_dwordx2 v0, v[162:163], s[4:5]
	v_fma_f32 v91, v91, v131, v138
	v_fma_f32 v95, v95, v131, v140
	v_fma_f32 v83, v83, v131, v134
	v_fma_f32 v87, v87, v131, v136
	v_cvt_pk_bf16_f32 v164, v91, v95
	v_cvt_pk_bf16_f32 v165, v83, v87
	global_store_dwordx2 v158, v[164:165], s[4:5]
	v_fma_f32 v92, v92, v132, v138
	v_fma_f32 v96, v96, v132, v140
	v_fma_f32 v84, v84, v132, v134
	v_fma_f32 v88, v88, v132, v136
	v_cvt_pk_bf16_f32 v166, v92, v96
	v_cvt_pk_bf16_f32 v167, v84, v88
	global_store_dwordx2 v159, v[166:167], s[4:5]
	v_fma_f32 v93, v93, v133, v138
	v_fma_f32 v97, v97, v133, v140
	v_fma_f32 v85, v85, v133, v134
	v_fma_f32 v89, v89, v133, v136
	v_cvt_pk_bf16_f32 v168, v93, v97
	v_cvt_pk_bf16_f32 v169, v85, v89
	global_store_dwordx2 v160, v[168:169], s[4:5]
	s_add_u32 s4, s4, 0x10000
	s_addc_u32 s5, s5, 0
	ds_read_b128 v[130:133], v154 offset:192
	s_waitcnt lgkmcnt(0)
; #define SCHED __builtin_amdgcn_sched_barrier(0)
; template <int EPI, bool HS = false>
; __device__ __forceinline__ void gemm_phase(const Params& p, const GemmCfg& g, char* shm, const int wave_s) {
;     ...
;         u16* ot = GOb + (size_t)orow0 * 2048 + (pn - 16) * 256;
;         const unsigned tb = (unsigned)((wr * 64 + fq * 4) * 2048 + wc * 32 + fr);
; #pragma unroll
;         for (int ai = 0; ai < 2; ++ai)
; #pragma unroll
;           for (int m = 0; m < 4; ++m) {
;             const f32x4 r4 = *(const f32x4*)(rsw + ai * 128 + m * 16);
; #pragma unroll
;             for (int j = 0; j < 4; ++j)
; #pragma unroll
;               for (int bj = 0; bj < 2; ++bj)
; #pragma unroll
;                 for (int n = 0; n < 2; ++n)
;                   ot[tb + (ai * 128 + m * 16 + j) * 2048 + bj * 128 + n * 16] = f2bf(r4[j] * acc[ai][bj][m][n][j] + swv[bj][n]);
;             SCHED;
;           }
	v_fma_f32 v74, v74, v130, v138
	v_fma_f32 v78, v78, v130, v140
	v_fma_f32 v66, v66, v130, v134
	v_fma_f32 v70, v70, v130, v136
	v_cvt_pk_bf16_f32 v162, v74, v78
	v_cvt_pk_bf16_f32 v163, v66, v70
	global_store_dwordx2 v0, v[162:163], s[4:5]
	v_fma_f32 v75, v75, v131, v138
	v_fma_f32 v79, v79, v131, v140
	v_fma_f32 v67, v67, v131, v134
	v_fma_f32 v71, v71, v131, v136
	v_cvt_pk_bf16_f32 v164, v75, v79
	v_cvt_pk_bf16_f32 v165, v67, v71
	global_store_dwordx2 v158, v[164:165], s[4:5]
	v_fma_f32 v76, v76, v132, v138
	v_fma_f32 v80, v80, v132, v140
	v_fma_f32 v68, v68, v132, v134
	v_fma_f32 v72, v72, v132, v136
	v_cvt_pk_bf16_f32 v166, v76, v80
	v_cvt_pk_bf16_f32 v167, v68, v72
	global_store_dwordx2 v159, v[166:167], s[4:5]
	v_fma_f32 v77, v77, v133, v138
	v_fma_f32 v81, v81, v133, v140
	v_fma_f32 v69, v69, v133, v134
	v_fma_f32 v73, v73, v133, v136
	v_cvt_pk_bf16_f32 v168, v77, v81
	v_cvt_pk_bf16_f32 v169, v69, v73
	global_store_dwordx2 v160, v[168:169], s[4:5]
	s_add_u32 s4, s4, 0x50000
	s_addc_u32 s5, s5, 0
	ds_read_b128 v[130:133], v154 offset:512
	s_waitcnt lgkmcnt(0)
	v_fma_f32 v58, v58, v130, v138
	v_fma_f32 v62, v62, v130, v140
	v_fma_f32 v50, v50, v130, v134
	v_fma_f32 v54, v54, v130, v136
	v_cvt_pk_bf16_f32 v162, v58, v62
	v_cvt_pk_bf16_f32 v163, v50, v54
	global_store_dwordx2 v0, v[162:163], s[4:5]
	v_fma_f32 v59, v59, v131, v138
	v_fma_f32 v63, v63, v131, v140
	v_fma_f32 v51, v51, v131, v134
	v_fma_f32 v55, v55, v131, v136
	v_cvt_pk_bf16_f32 v164, v59, v63
	v_cvt_pk_bf16_f32 v165, v51, v55
	global_store_dwordx2 v158, v[164:165], s[4:5]
	v_fma_f32 v60, v60, v132, v138
	v_fma_f32 v64, v64, v132, v140
	v_fma_f32 v52, v52, v132, v134
	v_fma_f32 v56, v56, v132, v136
	v_cvt_pk_bf16_f32 v166, v60, v64
	v_cvt_pk_bf16_f32 v167, v52, v56
	global_store_dwordx2 v159, v[166:167], s[4:5]
	v_fma_f32 v61, v61, v133, v138
	v_fma_f32 v65, v65, v133, v140
	v_fma_f32 v53, v53, v133, v134
	v_fma_f32 v57, v57, v133, v136
	v_cvt_pk_bf16_f32 v168, v61, v65
	v_cvt_pk_bf16_f32 v169, v53, v57
	global_store_dwordx2 v160, v[168:169], s[4:5]
	s_add_u32 s4, s4, 0x10000
	s_addc_u32 s5, s5, 0
	ds_read_b128 v[130:133], v154 offset:576
	s_waitcnt lgkmcnt(0)
	v_fma_f32 v42, v42, v130, v138
	v_fma_f32 v46, v46, v130, v140
	v_fma_f32 v34, v34, v130, v134
	v_fma_f32 v38, v38, v130, v136
	v_cvt_pk_bf16_f32 v162, v42, v46
	v_cvt_pk_bf16_f32 v163, v34, v38
	global_store_dwordx2 v0, v[162:163], s[4:5]
	v_fma_f32 v43, v43, v131, v138
	v_fma_f32 v47, v47, v131, v140
	v_fma_f32 v35, v35, v131, v134
	v_fma_f32 v39, v39, v131, v136
	v_cvt_pk_bf16_f32 v164, v43, v47
	v_cvt_pk_bf16_f32 v165, v35, v39
	global_store_dwordx2 v158, v[164:165], s[4:5]
	v_fma_f32 v44, v44, v132, v138
	v_fma_f32 v48, v48, v132, v140
	v_fma_f32 v36, v36, v132, v134
	v_fma_f32 v40, v40, v132, v136
	v_cvt_pk_bf16_f32 v166, v44, v48
	v_cvt_pk_bf16_f32 v167, v36, v40
	global_store_dwordx2 v159, v[166:167], s[4:5]
	v_fma_f32 v45, v45, v133, v138
	v_fma_f32 v49, v49, v133, v140
	v_fma_f32 v37, v37, v133, v134
	v_fma_f32 v41, v41, v133, v136
	v_cvt_pk_bf16_f32 v168, v45, v49
	v_cvt_pk_bf16_f32 v169, v37, v41
	global_store_dwordx2 v160, v[168:169], s[4:5]
	s_add_u32 s4, s4, 0x10000
	s_addc_u32 s5, s5, 0
	ds_read_b128 v[130:133], v154 offset:640
	s_waitcnt lgkmcnt(0)
	v_fma_f32 v26, v26, v130, v138
	v_fma_f32 v30, v30, v130, v140
	v_fma_f32 v18, v18, v130, v134
	v_fma_f32 v22, v22, v130, v136
	v_cvt_pk_bf16_f32 v162, v26, v30
	v_cvt_pk_bf16_f32 v163, v18, v22
	global_store_dwordx2 v0, v[162:163], s[4:5]
	v_fma_f32 v27, v27, v131, v138
	v_fma_f32 v31, v31, v131, v140
	v_fma_f32 v19, v19, v131, v134
	v_fma_f32 v23, v23, v131, v136
	v_cvt_pk_bf16_f32 v164, v27, v31
	v_cvt_pk_bf16_f32 v165, v19, v23
	global_store_dwordx2 v158, v[164:165], s[4:5]
	v_fma_f32 v28, v28, v132, v138
	v_fma_f32 v32, v32, v132, v140
	v_fma_f32 v20, v20, v132, v134
	v_fma_f32 v24, v24, v132, v136
	v_cvt_pk_bf16_f32 v166, v28, v32
	v_cvt_pk_bf16_f32 v167, v20, v24
	global_store_dwordx2 v159, v[166:167], s[4:5]
	v_fma_f32 v29, v29, v133, v138
	v_fma_f32 v33, v33, v133, v140
	v_fma_f32 v21, v21, v133, v134
	v_fma_f32 v25, v25, v133, v136
	v_cvt_pk_bf16_f32 v168, v29, v33
	v_cvt_pk_bf16_f32 v169, v21, v25
	global_store_dwordx2 v160, v[168:169], s[4:5]
	s_add_u32 s4, s4, 0x10000
	s_addc_u32 s5, s5, 0
	ds_read_b128 v[130:133], v154 offset:704
	s_waitcnt lgkmcnt(0)
	v_fma_f32 v10, v10, v130, v138
	v_fma_f32 v14, v14, v130, v140
	v_fma_f32 v2, v2, v130, v134
	v_fma_f32 v6, v6, v130, v136
	v_cvt_pk_bf16_f32 v162, v10, v14
	v_cvt_pk_bf16_f32 v163, v2, v6
	global_store_dwordx2 v0, v[162:163], s[4:5]
	v_fma_f32 v11, v11, v131, v138
	v_fma_f32 v15, v15, v131, v140
	v_fma_f32 v3, v3, v131, v134
	v_fma_f32 v7, v7, v131, v136
	v_cvt_pk_bf16_f32 v164, v11, v15
	v_cvt_pk_bf16_f32 v165, v3, v7
	global_store_dwordx2 v158, v[164:165], s[4:5]
	v_fma_f32 v12, v12, v132, v138
	v_fma_f32 v16, v16, v132, v140
	v_fma_f32 v4, v4, v132, v134
	v_fma_f32 v8, v8, v132, v136
	v_cvt_pk_bf16_f32 v166, v12, v16
	v_cvt_pk_bf16_f32 v167, v4, v8
	global_store_dwordx2 v159, v[166:167], s[4:5]
	v_fma_f32 v13, v13, v133, v138
	v_fma_f32 v17, v17, v133, v140
	v_fma_f32 v5, v5, v133, v134
	v_fma_f32 v9, v9, v133, v136
	v_cvt_pk_bf16_f32 v168, v13, v17
	v_cvt_pk_bf16_f32 v169, v5, v9
	global_store_dwordx2 v160, v[168:169], s[4:5]
	s_mov_b64 s[6:7], 0

; __device__ __forceinline__ int srccol(int perm, int n) {
;     ...
;   } else if (perm == 2) {
;     if (n < 2048) {
;       int part = n >> 10, hh = (n >> 8) & 3, cp = n & 255;
;       int grp = cp >> 5, t = (cp >> 4) & 1, i = cp & 15;
;       int pp = grp * 16 + i;
;       return part * 1024 + hh * 256 + t * 128 + pp;
;     }
;     return n;
; __device__ __forceinline__ void conv_family(const float* __restrict__ W, u16* __restrict__ Wt, int cnt, int K, int N, int perm,
;                             float* tile, const int tid, const float* __restrict__ kscale = nullptr) {
;     ...
;   for (int t = blockIdx.x; t < total; t += gridDim.x) {
;     int mi = t / per, r = t % per, kt = r / tn, ntile = r % tn;
;     const float* Ws = W + (size_t)mi * K * N;
;     u16* Wd = Wt + (size_t)mi * K * N;
;     int k0 = kt * 64, n0 = ntile * 256;
;     {
;       int n = tid & 255;
;       int sc = srccol(perm, n0 + n);
;       const float* wp = Ws + (size_t)(k0 + (tid >> 8)) * N + sc;
;       float v[32];
; #pragma unroll
;       for (int i = 0; i < 32; ++i) v[i] = wp[(size_t)(2 * i) * N];
.LBB0_915:
	s_mul_hi_i32 s0, s4, 0x2aaaaaab
	s_lshr_b32 s1, s0, 31
	s_ashr_i32 s0, s0, 6
	s_add_i32 s0, s0, s1
	s_mul_i32 s1, s0, 0xfffffe80
	s_add_i32 s1, s4, s1
	s_mul_i32 s2, s1, 0x2aab
	s_lshr_b32 s3, s2, 31
	s_ashr_i32 s2, s2, 18
	s_add_i32 s5, s2, s3
	s_mul_i32 s2, s5, 24
	s_sub_i32 s1, s1, s2
	s_sext_i32_i16 s8, s1
	s_mul_hi_i32 s1, s0, 0x600000
	s_mul_i32 s0, s0, 0x600000
	s_lshl_b64 s[2:3], s[0:1], 2
	s_add_u32 s2, s22, s2
	s_addc_u32 s3, s23, s3
	s_lshl_b64 s[0:1], s[0:1], 1
	s_add_u32 s6, s54, s0
	s_addc_u32 s7, s55, s1
	s_lshl_b32 s0, s5, 6
	s_lshl_b32 s5, s8, 8
	v_lshlrev_b32_e32 v9, 3, v3
	v_mov_b32_e32 v10, 0xffffff0f
	v_or_b32_e32 v8, s5, v3
	s_movk_i32 s1, 0x800
	v_and_b32_e32 v9, 0x80, v9
	v_bitop3_b32 v10, s5, v10, v3 bitop3:0xc8
	v_cmp_gt_i32_e32 vcc, s1, v8
	v_or3_b32 v9, v10, v5, v9
	v_mov_b64_e32 v[10:11], s[2:3]
	v_cndmask_b32_e32 v8, v8, v9, vcc
	v_bfe_u32 v12, v3, 5, 2
	v_lshlrev_b32_e32 v12, 6, v12
	v_and_b32_e32 v13, 15, v3
	v_lshl_add_u32 v12, v13, 2, v12
	v_bfe_u32 v13, v3, 7, 1
	v_lshl_add_u32 v12, v13, 1, v12
	v_bfe_u32 v13, v3, 4, 1
	v_add3_u32 v12, v12, v13, s5
	v_cmp_lt_u32_e32 vcc, 0xfff, v8
	s_nop 1
	v_cndmask_b32_e32 v8, v8, v12, vcc
	v_add_u32_e32 v9, s0, v4
	v_mad_i64_i32 v[10:11], s[2:3], v9, s10, v[10:11]
	v_ashrrev_i32_e32 v9, 31, v8
	v_lshl_add_u64 v[8:9], v[8:9], 2, v[10:11]
	v_add_co_u32_e32 v10, vcc, s12, v8
	global_load_dword v12, v[8:9], off
	s_nop 0
	v_addc_co_u32_e32 v11, vcc, 0, v9, vcc
	global_load_dword v13, v[10:11], off
	v_add_co_u32_e32 v10, vcc, s11, v8
	s_mov_b32 s1, 0xc0000
	s_nop 0
	v_addc_co_u32_e32 v11, vcc, 0, v9, vcc
	global_load_dword v14, v[10:11], off
	v_add_co_u32_e32 v10, vcc, s30, v8
	s_nop 1
	v_addc_co_u32_e32 v11, vcc, 0, v9, vcc
	global_load_dword v15, v[10:11], off
	v_add_co_u32_e32 v10, vcc, s56, v8
	s_nop 1
	v_addc_co_u32_e32 v11, vcc, 0, v9, vcc
	global_load_dword v16, v[10:11], off
	v_add_co_u32_e32 v10, vcc, s15, v8
	s_nop 1
	v_addc_co_u32_e32 v11, vcc, 0, v9, vcc
	global_load_dword v17, v[10:11], off
	v_add_co_u32_e32 v10, vcc, s34, v8
	s_nop 1
	v_addc_co_u32_e32 v11, vcc, 0, v9, vcc
	global_load_dword v18, v[10:11], off
	v_add_co_u32_e32 v10, vcc, s16, v8
	s_nop 1
	v_addc_co_u32_e32 v11, vcc, 0, v9, vcc
	global_load_dword v19, v[10:11], off
	v_add_co_u32_e32 v10, vcc, s17, v8
	s_nop 1
	v_addc_co_u32_e32 v11, vcc, 0, v9, vcc
	global_load_dword v20, v[10:11], off
	v_add_co_u32_e32 v10, vcc, s97, v8
	s_nop 1
	v_addc_co_u32_e32 v11, vcc, 0, v9, vcc
	global_load_dword v21, v[10:11], off
	v_add_co_u32_e32 v10, vcc, s18, v8
	s_nop 1
	v_addc_co_u32_e32 v11, vcc, 0, v9, vcc
	global_load_dword v22, v[10:11], off
	v_add_co_u32_e32 v10, vcc, s13, v8
	s_nop 1
	v_addc_co_u32_e32 v11, vcc, 0, v9, vcc
	global_load_dword v23, v[10:11], off
	v_add_co_u32_e32 v10, vcc, s9, v8
	s_nop 1
	v_addc_co_u32_e32 v11, vcc, 0, v9, vcc
	global_load_dword v24, v[10:11], off
	v_add_co_u32_e32 v10, vcc, s19, v8
	s_nop 1
	v_addc_co_u32_e32 v11, vcc, 0, v9, vcc
	global_load_dword v25, v[10:11], off
	v_add_co_u32_e32 v10, vcc, s20, v8
	s_nop 1
	v_addc_co_u32_e32 v11, vcc, 0, v9, vcc
	global_load_dword v26, v[10:11], off
	v_add_co_u32_e32 v10, vcc, s21, v8
	s_nop 1
	v_addc_co_u32_e32 v11, vcc, 0, v9, vcc
	global_load_dword v27, v[10:11], off
	v_add_co_u32_e32 v10, vcc, s1, v8
	s_mov_b32 s1, 0xcc000
	s_nop 0
	v_addc_co_u32_e32 v11, vcc, 0, v9, vcc
	global_load_dword v30, v[10:11], off
	v_add_co_u32_e32 v10, vcc, s1, v8
	s_mov_b32 s1, 0xd8000
	s_nop 0
	v_addc_co_u32_e32 v11, vcc, 0, v9, vcc
	global_load_dword v31, v[10:11], off
	v_add_co_u32_e32 v10, vcc, s1, v8
	s_mov_b32 s1, 0xe4000
	s_nop 0
	v_addc_co_u32_e32 v11, vcc, 0, v9, vcc
	global_load_dword v32, v[10:11], off
	v_add_co_u32_e32 v10, vcc, s1, v8
	s_mov_b32 s1, 0xf0000
	s_nop 0
	v_addc_co_u32_e32 v11, vcc, 0, v9, vcc
	global_load_dword v33, v[10:11], off
	v_add_co_u32_e32 v10, vcc, s1, v8
	s_mov_b32 s1, 0xfc000
	s_nop 0
	v_addc_co_u32_e32 v11, vcc, 0, v9, vcc
	global_load_dword v34, v[10:11], off
	v_add_co_u32_e32 v10, vcc, s1, v8
	s_mov_b32 s1, 0x114000
	s_nop 0
	v_addc_co_u32_e32 v11, vcc, 0, v9, vcc
	global_load_dword v35, v[10:11], off
	v_add_co_u32_e32 v10, vcc, s14, v8
	s_nop 1
	v_addc_co_u32_e32 v11, vcc, 0, v9, vcc
	global_load_dword v36, v[10:11], off
	v_add_co_u32_e32 v10, vcc, s1, v8
	s_mov_b32 s1, 0x120000
	s_nop 0
	v_addc_co_u32_e32 v11, vcc, 0, v9, vcc
	global_load_dword v37, v[10:11], off
	v_add_co_u32_e32 v10, vcc, s1, v8
	s_mov_b32 s1, 0x12c000
	s_nop 0
	v_addc_co_u32_e32 v11, vcc, 0, v9, vcc
	global_load_dword v38, v[10:11], off
	v_add_co_u32_e32 v10, vcc, s1, v8
	s_mov_b32 s1, 0x138000
	s_nop 0
	v_addc_co_u32_e32 v11, vcc, 0, v9, vcc
	global_load_dword v39, v[10:11], off
	v_add_co_u32_e32 v10, vcc, s1, v8
	s_mov_b32 s1, 0x144000
	s_nop 0
	v_addc_co_u32_e32 v11, vcc, 0, v9, vcc
	global_load_dword v40, v[10:11], off
	v_add_co_u32_e32 v10, vcc, s1, v8
	s_mov_b32 s1, 0x150000
	s_nop 0
	v_addc_co_u32_e32 v11, vcc, 0, v9, vcc
	global_load_dword v41, v[10:11], off
	v_add_co_u32_e32 v10, vcc, s1, v8
	s_mov_b32 s1, 0x15c000
	s_nop 0
	v_addc_co_u32_e32 v11, vcc, 0, v9, vcc
	global_load_dword v42, v[10:11], off
	v_add_co_u32_e32 v10, vcc, s1, v8
	s_mov_b32 s1, 0x168000
	s_nop 0
	v_addc_co_u32_e32 v11, vcc, 0, v9, vcc
	global_load_dword v43, v[10:11], off
	v_add_co_u32_e32 v10, vcc, s1, v8
	s_mov_b32 s1, 0x174000
	s_nop 0
	v_addc_co_u32_e32 v11, vcc, 0, v9, vcc
	v_add_co_u32_e32 v8, vcc, s1, v8
	global_load_dword v10, v[10:11], off
	s_nop 0
	v_addc_co_u32_e32 v9, vcc, 0, v9, vcc
	global_load_dword v8, v[8:9], off
	s_waitcnt vmcnt(31)
	ds_write_b32 v29, v12
	s_waitcnt vmcnt(30)
	ds_write_b32 v29, v13 offset:2056
	s_waitcnt vmcnt(29)
; __device__ __forceinline__ unsigned pack2(float a, float b) { return (unsigned)f2bf(a) | ((unsigned)f2bf(b) << 16); }
; __device__ __forceinline__ void conv_family(const float* __restrict__ W, u16* __restrict__ Wt, int cnt, int K, int N, int perm,
;                             float* tile, const int tid, const float* __restrict__ kscale = nullptr) {
;     ...
;       for (int i = 0; i < 32; ++i) tile[(2 * i + (tid >> 8)) * 257 + n] = v[i];
;     }
;     __syncthreads();
; #pragma unroll
;     for (int i = 0; i < 4; ++i) {
;       int n = i * 64 + (tid >> 3), ks = (tid & 7) * 8;
;       uint4 pk;
;       pk.x = pack2(tile[(ks + 0) * 257 + n], tile[(ks + 1) * 257 + n]);
;       pk.y = pack2(tile[(ks + 2) * 257 + n], tile[(ks + 3) * 257 + n]);
;       pk.z = pack2(tile[(ks + 4) * 257 + n], tile[(ks + 5) * 257 + n]);
;       pk.w = pack2(tile[(ks + 6) * 257 + n], tile[(ks + 7) * 257 + n]);
;       *(uint4*)(Wd + (size_t)(n0 + n) * K + k0 + ks) = pk;
;     }
	ds_write_b32 v29, v14 offset:4112
	s_waitcnt vmcnt(28)
	ds_write_b32 v29, v15 offset:6168
	s_waitcnt vmcnt(27)
	ds_write_b32 v29, v16 offset:8224
	s_waitcnt vmcnt(26)
	ds_write_b32 v29, v17 offset:10280
	s_waitcnt vmcnt(25)
	ds_write_b32 v29, v18 offset:12336
	s_waitcnt vmcnt(24)
	ds_write_b32 v29, v19 offset:14392
	s_waitcnt vmcnt(23)
	ds_write_b32 v29, v20 offset:16448
	s_waitcnt vmcnt(22)
	ds_write_b32 v29, v21 offset:18504
	s_waitcnt vmcnt(21)
	ds_write_b32 v29, v22 offset:20560
	s_waitcnt vmcnt(20)
	ds_write_b32 v29, v23 offset:22616
	s_waitcnt vmcnt(19)
	ds_write_b32 v29, v24 offset:24672
	s_waitcnt vmcnt(18)
	ds_write_b32 v29, v25 offset:26728
	s_waitcnt vmcnt(17)
	ds_write_b32 v29, v26 offset:28784
	s_waitcnt vmcnt(16)
	ds_write_b32 v29, v27 offset:30840
	s_waitcnt vmcnt(15)
	ds_write_b32 v29, v30 offset:32896
	s_waitcnt vmcnt(14)
	ds_write_b32 v29, v31 offset:34952
	s_waitcnt vmcnt(13)
	ds_write_b32 v29, v32 offset:37008
	s_waitcnt vmcnt(12)
	ds_write_b32 v29, v33 offset:39064
	s_waitcnt vmcnt(11)
	ds_write_b32 v29, v34 offset:41120
	s_waitcnt vmcnt(10)
	ds_write_b32 v29, v35 offset:43176
	s_waitcnt vmcnt(9)
	ds_write_b32 v29, v36 offset:45232
	s_waitcnt vmcnt(8)
	ds_write_b32 v29, v37 offset:47288
	s_waitcnt vmcnt(7)
	ds_write_b32 v29, v38 offset:49344
	s_waitcnt vmcnt(6)
	ds_write_b32 v29, v39 offset:51400
	s_waitcnt vmcnt(5)
	ds_write_b32 v29, v40 offset:53456
	s_waitcnt vmcnt(4)
	ds_write_b32 v29, v41 offset:55512
	s_waitcnt vmcnt(3)
	ds_write_b32 v29, v42 offset:57568
	s_waitcnt vmcnt(2)
	ds_write_b32 v29, v43 offset:59624
	s_waitcnt vmcnt(1)
	ds_write_b32 v29, v10 offset:61680
	s_waitcnt vmcnt(0)
	ds_write_b32 v29, v8 offset:63736
	v_add_u32_e32 v37, 8, v28
	s_waitcnt lgkmcnt(0)
	s_barrier
	ds_read2st64_b32 v[16:17], v37 offset0:8 offset1:9
	v_add_u32_e32 v38, 12, v28
	ds_read2st64_b32 v[18:19], v38 offset0:12 offset1:13
	s_ashr_i32 s1, s0, 31
	ds_read2st64_b32 v[10:11], v28 offset1:1
	v_add_u32_e32 v36, 4, v28
	s_lshl_b64 s[0:1], s[0:1], 1
	ds_read2st64_b32 v[14:15], v36 offset0:4 offset1:5
	v_add_u32_e32 v40, 20, v28
	v_add_u32_e32 v12, s5, v7
	s_add_u32 s0, s6, s0
	v_add_u32_e32 v39, 16, v28
	ds_read2st64_b32 v[22:23], v40 offset0:20 offset1:21
	v_ashrrev_i32_e32 v13, 31, v12
	s_addc_u32 s1, s7, s1
	ds_read2st64_b32 v[20:21], v39 offset0:16 offset1:17
	v_add_u32_e32 v42, 28, v28
	v_lshlrev_b64 v[30:31], 11, v[12:13]
	s_waitcnt lgkmcnt(5)
	v_and_b32_sdwa v13, v16, v178 dst_sel:DWORD dst_unused:UNUSED_PAD src0_sel:WORD_1 src1_sel:DWORD
	v_lshl_add_u64 v[8:9], s[0:1], 0, v[0:1]
	v_add_u32_e32 v41, 24, v28
	ds_read2st64_b32 v[26:27], v42 offset0:28 offset1:29
	v_add3_u32 v13, v16, v13, s81
	s_waitcnt lgkmcnt(5)
	v_and_b32_sdwa v16, v18, v178 dst_sel:DWORD dst_unused:UNUSED_PAD src0_sel:WORD_1 src1_sel:DWORD
	ds_read2st64_b32 v[24:25], v41 offset0:24 offset1:25
	v_lshl_add_u64 v[34:35], v[8:9], 0, v[30:31]
	s_waitcnt lgkmcnt(5)
	v_and_b32_sdwa v30, v10, v178 dst_sel:DWORD dst_unused:UNUSED_PAD src0_sel:WORD_1 src1_sel:DWORD
	v_add3_u32 v16, v18, v16, s81
	v_add3_u32 v10, v10, v30, s81
	s_waitcnt lgkmcnt(4)
	v_and_b32_sdwa v30, v14, v178 dst_sel:DWORD dst_unused:UNUSED_PAD src0_sel:WORD_1 src1_sel:DWORD
	v_and_b32_e32 v16, 0xffff0000, v16
	v_add3_u32 v14, v14, v30, s81
	v_or_b32_sdwa v31, v16, v13 dst_sel:DWORD dst_unused:UNUSED_PAD src0_sel:DWORD src1_sel:WORD_1
	s_waitcnt lgkmcnt(3)
	v_and_b32_sdwa v16, v22, v178 dst_sel:DWORD dst_unused:UNUSED_PAD src0_sel:WORD_1 src1_sel:DWORD
	v_and_b32_e32 v14, 0xffff0000, v14
	s_waitcnt lgkmcnt(2)
	v_and_b32_sdwa v13, v20, v178 dst_sel:DWORD dst_unused:UNUSED_PAD src0_sel:WORD_1 src1_sel:DWORD
	v_add3_u32 v16, v22, v16, s81
	v_or_b32_sdwa v30, v14, v10 dst_sel:DWORD dst_unused:UNUSED_PAD src0_sel:DWORD src1_sel:WORD_1
	v_add3_u32 v13, v20, v13, s81
	s_waitcnt lgkmcnt(1)
	v_and_b32_sdwa v14, v26, v178 dst_sel:DWORD dst_unused:UNUSED_PAD src0_sel:WORD_1 src1_sel:DWORD
	v_and_b32_e32 v16, 0xffff0000, v16
	s_waitcnt lgkmcnt(0)
; __device__ __forceinline__ unsigned pack2(float a, float b) { return (unsigned)f2bf(a) | ((unsigned)f2bf(b) << 16); }
; __device__ __forceinline__ void conv_family(const float* __restrict__ W, u16* __restrict__ Wt, int cnt, int K, int N, int perm,
;                             float* tile, const int tid, const float* __restrict__ kscale = nullptr) {
;     ...
;     for (int i = 0; i < 4; ++i) {
;       int n = i * 64 + (tid >> 3), ks = (tid & 7) * 8;
;       uint4 pk;
;       pk.x = pack2(tile[(ks + 0) * 257 + n], tile[(ks + 1) * 257 + n]);
;       pk.y = pack2(tile[(ks + 2) * 257 + n], tile[(ks + 3) * 257 + n]);
;       pk.z = pack2(tile[(ks + 4) * 257 + n], tile[(ks + 5) * 257 + n]);
;       pk.w = pack2(tile[(ks + 6) * 257 + n], tile[(ks + 7) * 257 + n]);
;       *(uint4*)(Wd + (size_t)(n0 + n) * K + k0 + ks) = pk;
;     }
;     __syncthreads();
;   }
	v_and_b32_sdwa v10, v24, v178 dst_sel:DWORD dst_unused:UNUSED_PAD src0_sel:WORD_1 src1_sel:DWORD
	v_add3_u32 v14, v26, v14, s81
	v_or_b32_sdwa v32, v16, v13 dst_sel:DWORD dst_unused:UNUSED_PAD src0_sel:DWORD src1_sel:WORD_1
	v_and_b32_sdwa v13, v11, v178 dst_sel:DWORD dst_unused:UNUSED_PAD src0_sel:WORD_1 src1_sel:DWORD
	v_add3_u32 v10, v24, v10, s81
	v_and_b32_e32 v14, 0xffff0000, v14
	v_add3_u32 v11, v11, v13, s81
	v_and_b32_sdwa v13, v19, v178 dst_sel:DWORD dst_unused:UNUSED_PAD src0_sel:WORD_1 src1_sel:DWORD
	v_or_b32_sdwa v33, v14, v10 dst_sel:DWORD dst_unused:UNUSED_PAD src0_sel:DWORD src1_sel:WORD_1
	v_and_b32_sdwa v10, v17, v178 dst_sel:DWORD dst_unused:UNUSED_PAD src0_sel:WORD_1 src1_sel:DWORD
	v_and_b32_sdwa v14, v15, v178 dst_sel:DWORD dst_unused:UNUSED_PAD src0_sel:WORD_1 src1_sel:DWORD
	v_add3_u32 v13, v19, v13, s81
	v_add3_u32 v10, v17, v10, s81
	v_add3_u32 v14, v15, v14, s81
	v_and_b32_e32 v13, 0xffff0000, v13
	global_store_dwordx4 v[34:35], v[30:33], off
	v_and_b32_e32 v14, 0xffff0000, v14
	v_or_b32_sdwa v15, v13, v10 dst_sel:DWORD dst_unused:UNUSED_PAD src0_sel:DWORD src1_sel:WORD_1
	v_add_u32_e32 v30, 64, v12
	v_and_b32_sdwa v13, v27, v178 dst_sel:DWORD dst_unused:UNUSED_PAD src0_sel:WORD_1 src1_sel:DWORD
	v_and_b32_sdwa v16, v23, v178 dst_sel:DWORD dst_unused:UNUSED_PAD src0_sel:WORD_1 src1_sel:DWORD
	v_ashrrev_i32_e32 v31, 31, v30
	v_or_b32_sdwa v14, v14, v11 dst_sel:DWORD dst_unused:UNUSED_PAD src0_sel:DWORD src1_sel:WORD_1
	v_and_b32_sdwa v10, v25, v178 dst_sel:DWORD dst_unused:UNUSED_PAD src0_sel:WORD_1 src1_sel:DWORD
	v_and_b32_sdwa v11, v21, v178 dst_sel:DWORD dst_unused:UNUSED_PAD src0_sel:WORD_1 src1_sel:DWORD
	v_add3_u32 v13, v27, v13, s81
	v_add3_u32 v16, v23, v16, s81
	v_lshlrev_b64 v[30:31], 11, v[30:31]
	v_add3_u32 v11, v21, v11, s81
	v_add3_u32 v10, v25, v10, s81
	v_and_b32_e32 v13, 0xffff0000, v13
	v_and_b32_e32 v16, 0xffff0000, v16
	v_lshl_add_u64 v[30:31], v[8:9], 0, v[30:31]
	v_or_b32_sdwa v17, v13, v10 dst_sel:DWORD dst_unused:UNUSED_PAD src0_sel:DWORD src1_sel:WORD_1
	v_or_b32_sdwa v16, v16, v11 dst_sel:DWORD dst_unused:UNUSED_PAD src0_sel:DWORD src1_sel:WORD_1
	global_store_dwordx4 v[30:31], v[14:17], off
	ds_read2st64_b32 v[24:25], v28 offset0:2 offset1:3
	ds_read2st64_b32 v[20:21], v36 offset0:6 offset1:7
	ds_read2st64_b32 v[26:27], v37 offset0:10 offset1:11
	ds_read2st64_b32 v[22:23], v38 offset0:14 offset1:15
	ds_read2st64_b32 v[16:17], v39 offset0:18 offset1:19
	ds_read2st64_b32 v[10:11], v40 offset0:22 offset1:23
	ds_read2st64_b32 v[18:19], v41 offset0:26 offset1:27
	ds_read2st64_b32 v[14:15], v42 offset0:30 offset1:31
	v_add_u32_e32 v30, 0x80, v12
	s_waitcnt lgkmcnt(5)
	v_and_b32_sdwa v13, v26, v178 dst_sel:DWORD dst_unused:UNUSED_PAD src0_sel:WORD_1 src1_sel:DWORD
	v_ashrrev_i32_e32 v31, 31, v30
	v_add3_u32 v13, v26, v13, s81
	s_waitcnt lgkmcnt(4)
	v_and_b32_sdwa v26, v22, v178 dst_sel:DWORD dst_unused:UNUSED_PAD src0_sel:WORD_1 src1_sel:DWORD
	v_lshlrev_b64 v[30:31], 11, v[30:31]
	v_add3_u32 v22, v22, v26, s81
	v_lshl_add_u64 v[34:35], v[8:9], 0, v[30:31]
	v_and_b32_sdwa v30, v24, v178 dst_sel:DWORD dst_unused:UNUSED_PAD src0_sel:WORD_1 src1_sel:DWORD
	v_and_b32_e32 v22, 0xffff0000, v22
	v_add3_u32 v24, v24, v30, s81
	v_and_b32_sdwa v30, v20, v178 dst_sel:DWORD dst_unused:UNUSED_PAD src0_sel:WORD_1 src1_sel:DWORD
	v_or_b32_sdwa v31, v22, v13 dst_sel:DWORD dst_unused:UNUSED_PAD src0_sel:DWORD src1_sel:WORD_1
	s_waitcnt lgkmcnt(1)
	v_and_b32_sdwa v13, v18, v178 dst_sel:DWORD dst_unused:UNUSED_PAD src0_sel:WORD_1 src1_sel:DWORD
	v_add3_u32 v20, v20, v30, s81
	v_add3_u32 v13, v18, v13, s81
	s_waitcnt lgkmcnt(0)
	v_and_b32_sdwa v18, v14, v178 dst_sel:DWORD dst_unused:UNUSED_PAD src0_sel:WORD_1 src1_sel:DWORD
	v_and_b32_e32 v20, 0xffff0000, v20
	v_add3_u32 v14, v14, v18, s81
	v_or_b32_sdwa v30, v20, v24 dst_sel:DWORD dst_unused:UNUSED_PAD src0_sel:DWORD src1_sel:WORD_1
	v_and_b32_sdwa v20, v16, v178 dst_sel:DWORD dst_unused:UNUSED_PAD src0_sel:WORD_1 src1_sel:DWORD
	v_and_b32_e32 v14, 0xffff0000, v14
	v_add_u32_e32 v12, 0xc0, v12
	v_add3_u32 v16, v16, v20, s81
	v_and_b32_sdwa v20, v10, v178 dst_sel:DWORD dst_unused:UNUSED_PAD src0_sel:WORD_1 src1_sel:DWORD
	v_or_b32_sdwa v33, v14, v13 dst_sel:DWORD dst_unused:UNUSED_PAD src0_sel:DWORD src1_sel:WORD_1
	v_ashrrev_i32_e32 v13, 31, v12
	v_add3_u32 v10, v10, v20, s81
	v_lshlrev_b64 v[12:13], 11, v[12:13]
	v_and_b32_e32 v10, 0xffff0000, v10
	v_lshl_add_u64 v[12:13], v[8:9], 0, v[12:13]
	v_and_b32_sdwa v9, v25, v178 dst_sel:DWORD dst_unused:UNUSED_PAD src0_sel:WORD_1 src1_sel:DWORD
	v_or_b32_sdwa v32, v10, v16 dst_sel:DWORD dst_unused:UNUSED_PAD src0_sel:DWORD src1_sel:WORD_1
	v_add3_u32 v10, v25, v9, s81
	v_and_b32_sdwa v9, v23, v178 dst_sel:DWORD dst_unused:UNUSED_PAD src0_sel:WORD_1 src1_sel:DWORD
	v_and_b32_sdwa v14, v21, v178 dst_sel:DWORD dst_unused:UNUSED_PAD src0_sel:WORD_1 src1_sel:DWORD
	v_and_b32_sdwa v8, v27, v178 dst_sel:DWORD dst_unused:UNUSED_PAD src0_sel:WORD_1 src1_sel:DWORD
	v_add3_u32 v9, v23, v9, s81
	v_add3_u32 v14, v21, v14, s81
	v_add3_u32 v8, v27, v8, s81
	v_and_b32_e32 v9, 0xffff0000, v9
	v_and_b32_e32 v14, 0xffff0000, v14
	v_or_b32_sdwa v9, v9, v8 dst_sel:DWORD dst_unused:UNUSED_PAD src0_sel:DWORD src1_sel:WORD_1
	v_or_b32_sdwa v8, v14, v10 dst_sel:DWORD dst_unused:UNUSED_PAD src0_sel:DWORD src1_sel:WORD_1
	v_and_b32_sdwa v14, v17, v178 dst_sel:DWORD dst_unused:UNUSED_PAD src0_sel:WORD_1 src1_sel:DWORD
	v_add3_u32 v14, v17, v14, s81
	v_and_b32_sdwa v16, v15, v178 dst_sel:DWORD dst_unused:UNUSED_PAD src0_sel:WORD_1 src1_sel:DWORD
	v_and_b32_sdwa v17, v11, v178 dst_sel:DWORD dst_unused:UNUSED_PAD src0_sel:WORD_1 src1_sel:DWORD
	v_and_b32_sdwa v10, v19, v178 dst_sel:DWORD dst_unused:UNUSED_PAD src0_sel:WORD_1 src1_sel:DWORD
	v_add3_u32 v15, v15, v16, s81
	v_add3_u32 v11, v11, v17, s81
	v_add3_u32 v10, v19, v10, s81
	v_and_b32_e32 v15, 0xffff0000, v15
	v_and_b32_e32 v16, 0xffff0000, v11
	s_add_i32 s4, s4, s44
	v_or_b32_sdwa v11, v15, v10 dst_sel:DWORD dst_unused:UNUSED_PAD src0_sel:DWORD src1_sel:WORD_1
	v_or_b32_sdwa v10, v16, v14 dst_sel:DWORD dst_unused:UNUSED_PAD src0_sel:DWORD src1_sel:WORD_1
	s_cmpk_lt_i32 s4, 0x300
	global_store_dwordx4 v[34:35], v[30:33], off
	global_store_dwordx4 v[12:13], v[8:11], off
	s_barrier
	s_cbranch_scc1 .LBB0_915
	s_mov_b32 s38, 0x1e000
	s_mov_b32 s39, 0x2c000
	s_mov_b32 s40, 0x22000
	s_mov_b32 s41, 0x26000
	s_mov_b32 s43, 0x2a000
	s_mov_b32 s48, 0x2e000
	s_mov_b32 s54, 0x32000
	s_mov_b32 s55, 0x34000
	s_mov_b32 s57, 0x38000
